# P8 epilogue rewritten by hand: all H/PROJ/ssq loads pipelined 4 blocks deep, single waits
# baseline (speedup 1.0000x reference)
.LBB0_1359:
	v_lshl_add_u32 v255, s8, 8, v188
	v_lshl_add_u32 v246, s30, 8, v190
	v_lshlrev_b32_e32 v244, 2, v255
	v_lshlrev_b32_e32 v245, 12, v255
	v_lshl_add_u32 v245, v246, 1, v245
	v_lshlrev_b32_e32 v247, 2, v246
	global_load_dword v228, v244, s[12:13] offset:0
	global_load_dword v229, v244, s[12:13] offset:64
	global_load_dword v230, v244, s[12:13] offset:128
	global_load_dword v231, v244, s[12:13] offset:192
	global_load_dword v232, v244, s[12:13] offset:512
	global_load_dword v233, v244, s[12:13] offset:576
	global_load_dword v234, v244, s[12:13] offset:640
	global_load_dword v235, v244, s[12:13] offset:704
	global_load_dwordx4 v[144:147], v245, s[52:53]
	global_load_dwordx4 v[148:151], v245, s[58:59]
	global_load_dwordx4 v[152:155], v245, s[52:53] offset:256
	global_load_dwordx4 v[156:159], v245, s[58:59] offset:256
	v_add_u32_e32 v246, 0x10000, v245
	global_load_dwordx4 v[160:163], v246, s[52:53]
	global_load_dwordx4 v[164:167], v246, s[58:59]
	global_load_dwordx4 v[168:171], v246, s[52:53] offset:256
	global_load_dwordx4 v[172:175], v246, s[58:59] offset:256
	v_add_u32_e32 v246, 0x20000, v245
	global_load_dwordx4 v[176:179], v246, s[52:53]
	global_load_dwordx4 v[180:183], v246, s[58:59]
	global_load_dwordx4 v[184:187], v246, s[52:53] offset:256
	global_load_dwordx4 v[196:199], v246, s[58:59] offset:256
	v_add_u32_e32 v246, 0x30000, v245
	global_load_dwordx4 v[200:203], v246, s[52:53]
	global_load_dwordx4 v[204:207], v246, s[58:59]
	global_load_dwordx4 v[208:211], v246, s[52:53] offset:256
	global_load_dwordx4 v[212:215], v246, s[58:59] offset:256
	v_mov_b32_e32 v248, 0xbfb8aa3b
	v_mov_b32_e32 v249, 0x45800000
	v_xor_b32_e32 v251, 16, v194
	v_xor_b32_e32 v254, 32, v194
	v_lshlrev_b32_e32 v251, 2, v251
	v_lshlrev_b32_e32 v254, 2, v254
	s_waitcnt vmcnt(16)
	v_fmamk_f32 v228, v228, 0x3a000000, v195
	v_fmamk_f32 v229, v229, 0x3a000000, v195
	v_fmamk_f32 v230, v230, 0x3a000000, v195
	v_fmamk_f32 v231, v231, 0x3a000000, v195
	v_fmamk_f32 v232, v232, 0x3a000000, v195
	v_fmamk_f32 v233, v233, 0x3a000000, v195
	v_fmamk_f32 v234, v234, 0x3a000000, v195
	v_fmamk_f32 v235, v235, 0x3a000000, v195
	v_mul_f32_e32 v236, 0x4b800000, v228
	v_mul_f32_e32 v237, 0x4b800000, v229
	v_mul_f32_e32 v238, 0x4b800000, v230
	v_mul_f32_e32 v239, 0x4b800000, v231
	v_mul_f32_e32 v240, 0x4b800000, v232
	v_mul_f32_e32 v241, 0x4b800000, v233
	v_mul_f32_e32 v242, 0x4b800000, v234
	v_mul_f32_e32 v243, 0x4b800000, v235
	v_cmp_gt_f32_e32 vcc, s61, v228
	s_nop 1
	v_cndmask_b32_e32 v228, v228, v236, vcc
	v_cndmask_b32_e32 v236, 1.0, v249, vcc
	v_cmp_gt_f32_e32 vcc, s61, v229
	s_nop 1
	v_cndmask_b32_e32 v229, v229, v237, vcc
	v_cndmask_b32_e32 v237, 1.0, v249, vcc
	v_cmp_gt_f32_e32 vcc, s61, v230
	s_nop 1
	v_cndmask_b32_e32 v230, v230, v238, vcc
	v_cndmask_b32_e32 v238, 1.0, v249, vcc
	v_cmp_gt_f32_e32 vcc, s61, v231
	s_nop 1
	v_cndmask_b32_e32 v231, v231, v239, vcc
	v_cndmask_b32_e32 v239, 1.0, v249, vcc
	v_cmp_gt_f32_e32 vcc, s61, v232
	s_nop 1
	v_cndmask_b32_e32 v232, v232, v240, vcc
	v_cndmask_b32_e32 v240, 1.0, v249, vcc
	v_cmp_gt_f32_e32 vcc, s61, v233
	s_nop 1
	v_cndmask_b32_e32 v233, v233, v241, vcc
	v_cndmask_b32_e32 v241, 1.0, v249, vcc
	v_cmp_gt_f32_e32 vcc, s61, v234
	s_nop 1
	v_cndmask_b32_e32 v234, v234, v242, vcc
	v_cndmask_b32_e32 v242, 1.0, v249, vcc
	v_cmp_gt_f32_e32 vcc, s61, v235
	s_nop 1
	v_cndmask_b32_e32 v235, v235, v243, vcc
	v_cndmask_b32_e32 v243, 1.0, v249, vcc
	v_rsq_f32_e32 v228, v228
	v_rsq_f32_e32 v229, v229
	v_rsq_f32_e32 v230, v230
	v_rsq_f32_e32 v231, v231
	v_rsq_f32_e32 v232, v232
	v_rsq_f32_e32 v233, v233
	v_rsq_f32_e32 v234, v234
	v_rsq_f32_e32 v235, v235
	s_nop 0
	v_mul_f32_e32 v228, v228, v236
	v_mul_f32_e32 v229, v229, v237
	v_mul_f32_e32 v230, v230, v238
	v_mul_f32_e32 v231, v231, v239
	v_mul_f32_e32 v232, v232, v240
	v_mul_f32_e32 v233, v233, v241
	v_mul_f32_e32 v234, v234, v242
	v_mul_f32_e32 v235, v235, v243
	s_waitcnt vmcnt(12)
	v_mov_b32_e32 v226, v228
	v_pk_mul_f32 v[112:113], v[112:113], v[226:227] op_sel_hi:[1,0]
	v_pk_mul_f32 v[114:115], v[114:115], v[226:227] op_sel_hi:[1,0]
	v_pk_mul_f32 v[116:117], v[116:117], v[226:227] op_sel_hi:[1,0]
	v_pk_mul_f32 v[118:119], v[118:119], v[226:227] op_sel_hi:[1,0]
	v_pk_mul_f32 v[120:121], v[120:121], v[226:227] op_sel_hi:[1,0]
	v_pk_mul_f32 v[122:123], v[122:123], v[226:227] op_sel_hi:[1,0]
	v_pk_mul_f32 v[124:125], v[124:125], v[226:227] op_sel_hi:[1,0]
	v_pk_mul_f32 v[126:127], v[126:127], v[226:227] op_sel_hi:[1,0]
	v_pk_mul_f32 v[112:113], v[112:113], v[248:249] op_sel_hi:[1,0]
	v_pk_mul_f32 v[114:115], v[114:115], v[248:249] op_sel_hi:[1,0]
	v_pk_mul_f32 v[116:117], v[116:117], v[248:249] op_sel_hi:[1,0]
	v_pk_mul_f32 v[118:119], v[118:119], v[248:249] op_sel_hi:[1,0]
	v_pk_mul_f32 v[120:121], v[120:121], v[248:249] op_sel_hi:[1,0]
	v_pk_mul_f32 v[122:123], v[122:123], v[248:249] op_sel_hi:[1,0]
	v_pk_mul_f32 v[124:125], v[124:125], v[248:249] op_sel_hi:[1,0]
	v_pk_mul_f32 v[126:127], v[126:127], v[248:249] op_sel_hi:[1,0]
	v_exp_f32_e32 v112, v112
	v_exp_f32_e32 v113, v113
	v_exp_f32_e32 v114, v114
	v_exp_f32_e32 v115, v115
	v_exp_f32_e32 v116, v116
	v_exp_f32_e32 v117, v117
	v_exp_f32_e32 v118, v118
	v_exp_f32_e32 v119, v119
	v_exp_f32_e32 v120, v120
	v_exp_f32_e32 v121, v121
	v_exp_f32_e32 v122, v122
	v_exp_f32_e32 v123, v123
	v_exp_f32_e32 v124, v124
	v_exp_f32_e32 v125, v125
	v_exp_f32_e32 v126, v126
	v_exp_f32_e32 v127, v127
	v_pk_add_f32 v[112:113], v[112:113], 1.0 op_sel_hi:[1,0]
	v_pk_add_f32 v[114:115], v[114:115], 1.0 op_sel_hi:[1,0]
	v_pk_add_f32 v[116:117], v[116:117], 1.0 op_sel_hi:[1,0]
	v_pk_add_f32 v[118:119], v[118:119], 1.0 op_sel_hi:[1,0]
	v_pk_add_f32 v[120:121], v[120:121], 1.0 op_sel_hi:[1,0]
	v_pk_add_f32 v[122:123], v[122:123], 1.0 op_sel_hi:[1,0]
	v_pk_add_f32 v[124:125], v[124:125], 1.0 op_sel_hi:[1,0]
	v_pk_add_f32 v[126:127], v[126:127], 1.0 op_sel_hi:[1,0]
	v_rcp_f32_e32 v112, v112
	v_rcp_f32_e32 v113, v113
	v_rcp_f32_e32 v114, v114
	v_rcp_f32_e32 v115, v115
	v_rcp_f32_e32 v116, v116
	v_rcp_f32_e32 v117, v117
	v_rcp_f32_e32 v118, v118
	v_rcp_f32_e32 v119, v119
	v_rcp_f32_e32 v120, v120
	v_rcp_f32_e32 v121, v121
	v_rcp_f32_e32 v122, v122
	v_rcp_f32_e32 v123, v123
	v_rcp_f32_e32 v124, v124
	v_rcp_f32_e32 v125, v125
	v_rcp_f32_e32 v126, v126
	v_rcp_f32_e32 v127, v127
	v_lshlrev_b32_e32 v216, 16, v144
	v_and_b32_e32 v217, 0xffff0000, v144
	v_lshlrev_b32_e32 v236, 16, v148
	v_and_b32_e32 v237, 0xffff0000, v148
	v_lshlrev_b32_e32 v218, 16, v145
	v_and_b32_e32 v219, 0xffff0000, v145
	v_lshlrev_b32_e32 v238, 16, v149
	v_and_b32_e32 v239, 0xffff0000, v149
	v_lshlrev_b32_e32 v220, 16, v146
	v_and_b32_e32 v221, 0xffff0000, v146
	v_lshlrev_b32_e32 v240, 16, v150
	v_and_b32_e32 v241, 0xffff0000, v150
	v_lshlrev_b32_e32 v222, 16, v147
	v_and_b32_e32 v223, 0xffff0000, v147
	v_lshlrev_b32_e32 v242, 16, v151
	v_and_b32_e32 v243, 0xffff0000, v151
	v_pk_fma_f32 v[124:125], v[124:125], v[236:237], v[216:217]
	v_pk_fma_f32 v[126:127], v[126:127], v[238:239], v[218:219]
	v_pk_fma_f32 v[120:121], v[120:121], v[240:241], v[220:221]
	v_pk_fma_f32 v[122:123], v[122:123], v[242:243], v[222:223]
	v_pk_mul_f32 v[252:253], v[124:125], v[124:125]
	v_pk_fma_f32 v[252:253], v[126:127], v[126:127], v[252:253]
	v_pk_fma_f32 v[252:253], v[120:121], v[120:121], v[252:253]
	v_pk_fma_f32 v[252:253], v[122:123], v[122:123], v[252:253]
	v_lshlrev_b32_e32 v216, 16, v152
	v_and_b32_e32 v217, 0xffff0000, v152
	v_lshlrev_b32_e32 v236, 16, v156
	v_and_b32_e32 v237, 0xffff0000, v156
	v_lshlrev_b32_e32 v218, 16, v153
	v_and_b32_e32 v219, 0xffff0000, v153
	v_lshlrev_b32_e32 v238, 16, v157
	v_and_b32_e32 v239, 0xffff0000, v157
	v_lshlrev_b32_e32 v220, 16, v154
	v_and_b32_e32 v221, 0xffff0000, v154
	v_lshlrev_b32_e32 v240, 16, v158
	v_and_b32_e32 v241, 0xffff0000, v158
	v_lshlrev_b32_e32 v222, 16, v155
	v_and_b32_e32 v223, 0xffff0000, v155
	v_lshlrev_b32_e32 v242, 16, v159
	v_and_b32_e32 v243, 0xffff0000, v159
	v_pk_fma_f32 v[116:117], v[116:117], v[236:237], v[216:217]
	v_pk_fma_f32 v[118:119], v[118:119], v[238:239], v[218:219]
	v_pk_fma_f32 v[112:113], v[112:113], v[240:241], v[220:221]
	v_pk_fma_f32 v[114:115], v[114:115], v[242:243], v[222:223]
	v_pk_fma_f32 v[252:253], v[116:117], v[116:117], v[252:253]
	v_pk_fma_f32 v[252:253], v[118:119], v[118:119], v[252:253]
	v_pk_fma_f32 v[252:253], v[112:113], v[112:113], v[252:253]
	v_pk_fma_f32 v[252:253], v[114:115], v[114:115], v[252:253]
	v_add_f32_e32 v228, v252, v253
	v_add_u32_e32 v246, 0x80000, v245
	global_load_dwordx4 v[144:147], v246, s[52:53]
	global_load_dwordx4 v[148:151], v246, s[58:59]
	global_load_dwordx4 v[152:155], v246, s[52:53] offset:256
	global_load_dwordx4 v[156:159], v246, s[58:59] offset:256
	s_waitcnt vmcnt(12)
	v_mov_b32_e32 v226, v229
	v_pk_mul_f32 v[96:97], v[96:97], v[226:227] op_sel_hi:[1,0]
	v_pk_mul_f32 v[98:99], v[98:99], v[226:227] op_sel_hi:[1,0]
	v_pk_mul_f32 v[100:101], v[100:101], v[226:227] op_sel_hi:[1,0]
	v_pk_mul_f32 v[102:103], v[102:103], v[226:227] op_sel_hi:[1,0]
	v_pk_mul_f32 v[104:105], v[104:105], v[226:227] op_sel_hi:[1,0]
	v_pk_mul_f32 v[106:107], v[106:107], v[226:227] op_sel_hi:[1,0]
	v_pk_mul_f32 v[108:109], v[108:109], v[226:227] op_sel_hi:[1,0]
	v_pk_mul_f32 v[110:111], v[110:111], v[226:227] op_sel_hi:[1,0]
	v_pk_mul_f32 v[96:97], v[96:97], v[248:249] op_sel_hi:[1,0]
	v_pk_mul_f32 v[98:99], v[98:99], v[248:249] op_sel_hi:[1,0]
	v_pk_mul_f32 v[100:101], v[100:101], v[248:249] op_sel_hi:[1,0]
	v_pk_mul_f32 v[102:103], v[102:103], v[248:249] op_sel_hi:[1,0]
	v_pk_mul_f32 v[104:105], v[104:105], v[248:249] op_sel_hi:[1,0]
	v_pk_mul_f32 v[106:107], v[106:107], v[248:249] op_sel_hi:[1,0]
	v_pk_mul_f32 v[108:109], v[108:109], v[248:249] op_sel_hi:[1,0]
	v_pk_mul_f32 v[110:111], v[110:111], v[248:249] op_sel_hi:[1,0]
	v_exp_f32_e32 v96, v96
	v_exp_f32_e32 v97, v97
	v_exp_f32_e32 v98, v98
	v_exp_f32_e32 v99, v99
	v_exp_f32_e32 v100, v100
	v_exp_f32_e32 v101, v101
	v_exp_f32_e32 v102, v102
	v_exp_f32_e32 v103, v103
	v_exp_f32_e32 v104, v104
	v_exp_f32_e32 v105, v105
	v_exp_f32_e32 v106, v106
	v_exp_f32_e32 v107, v107
	v_exp_f32_e32 v108, v108
	v_exp_f32_e32 v109, v109
	v_exp_f32_e32 v110, v110
	v_exp_f32_e32 v111, v111
	v_pk_add_f32 v[96:97], v[96:97], 1.0 op_sel_hi:[1,0]
	v_pk_add_f32 v[98:99], v[98:99], 1.0 op_sel_hi:[1,0]
	v_pk_add_f32 v[100:101], v[100:101], 1.0 op_sel_hi:[1,0]
	v_pk_add_f32 v[102:103], v[102:103], 1.0 op_sel_hi:[1,0]
	v_pk_add_f32 v[104:105], v[104:105], 1.0 op_sel_hi:[1,0]
	v_pk_add_f32 v[106:107], v[106:107], 1.0 op_sel_hi:[1,0]
	v_pk_add_f32 v[108:109], v[108:109], 1.0 op_sel_hi:[1,0]
	v_pk_add_f32 v[110:111], v[110:111], 1.0 op_sel_hi:[1,0]
	v_rcp_f32_e32 v96, v96
	v_rcp_f32_e32 v97, v97
	v_rcp_f32_e32 v98, v98
	v_rcp_f32_e32 v99, v99
	v_rcp_f32_e32 v100, v100
	v_rcp_f32_e32 v101, v101
	v_rcp_f32_e32 v102, v102
	v_rcp_f32_e32 v103, v103
	v_rcp_f32_e32 v104, v104
	v_rcp_f32_e32 v105, v105
	v_rcp_f32_e32 v106, v106
	v_rcp_f32_e32 v107, v107
	v_rcp_f32_e32 v108, v108
	v_rcp_f32_e32 v109, v109
	v_rcp_f32_e32 v110, v110
	v_rcp_f32_e32 v111, v111
	v_lshlrev_b32_e32 v216, 16, v160
	v_and_b32_e32 v217, 0xffff0000, v160
	v_lshlrev_b32_e32 v236, 16, v164
	v_and_b32_e32 v237, 0xffff0000, v164
	v_lshlrev_b32_e32 v218, 16, v161
	v_and_b32_e32 v219, 0xffff0000, v161
	v_lshlrev_b32_e32 v238, 16, v165
	v_and_b32_e32 v239, 0xffff0000, v165
	v_lshlrev_b32_e32 v220, 16, v162
	v_and_b32_e32 v221, 0xffff0000, v162
	v_lshlrev_b32_e32 v240, 16, v166
	v_and_b32_e32 v241, 0xffff0000, v166
	v_lshlrev_b32_e32 v222, 16, v163
	v_and_b32_e32 v223, 0xffff0000, v163
	v_lshlrev_b32_e32 v242, 16, v167
	v_and_b32_e32 v243, 0xffff0000, v167
	v_pk_fma_f32 v[108:109], v[108:109], v[236:237], v[216:217]
	v_pk_fma_f32 v[110:111], v[110:111], v[238:239], v[218:219]
	v_pk_fma_f32 v[104:105], v[104:105], v[240:241], v[220:221]
	v_pk_fma_f32 v[106:107], v[106:107], v[242:243], v[222:223]
	v_pk_mul_f32 v[252:253], v[108:109], v[108:109]
	v_pk_fma_f32 v[252:253], v[110:111], v[110:111], v[252:253]
	v_pk_fma_f32 v[252:253], v[104:105], v[104:105], v[252:253]
	v_pk_fma_f32 v[252:253], v[106:107], v[106:107], v[252:253]
	v_lshlrev_b32_e32 v216, 16, v168
	v_and_b32_e32 v217, 0xffff0000, v168
	v_lshlrev_b32_e32 v236, 16, v172
	v_and_b32_e32 v237, 0xffff0000, v172
	v_lshlrev_b32_e32 v218, 16, v169
	v_and_b32_e32 v219, 0xffff0000, v169
	v_lshlrev_b32_e32 v238, 16, v173
	v_and_b32_e32 v239, 0xffff0000, v173
	v_lshlrev_b32_e32 v220, 16, v170
	v_and_b32_e32 v221, 0xffff0000, v170
	v_lshlrev_b32_e32 v240, 16, v174
	v_and_b32_e32 v241, 0xffff0000, v174
	v_lshlrev_b32_e32 v222, 16, v171
	v_and_b32_e32 v223, 0xffff0000, v171
	v_lshlrev_b32_e32 v242, 16, v175
	v_and_b32_e32 v243, 0xffff0000, v175
	v_pk_fma_f32 v[100:101], v[100:101], v[236:237], v[216:217]
	v_pk_fma_f32 v[102:103], v[102:103], v[238:239], v[218:219]
	v_pk_fma_f32 v[96:97], v[96:97], v[240:241], v[220:221]
	v_pk_fma_f32 v[98:99], v[98:99], v[242:243], v[222:223]
	v_pk_fma_f32 v[252:253], v[100:101], v[100:101], v[252:253]
	v_pk_fma_f32 v[252:253], v[102:103], v[102:103], v[252:253]
	v_pk_fma_f32 v[252:253], v[96:97], v[96:97], v[252:253]
	v_pk_fma_f32 v[252:253], v[98:99], v[98:99], v[252:253]
	v_add_f32_e32 v229, v252, v253
	v_add_u32_e32 v246, 0x90000, v245
	global_load_dwordx4 v[160:163], v246, s[52:53]
	global_load_dwordx4 v[164:167], v246, s[58:59]
	global_load_dwordx4 v[168:171], v246, s[52:53] offset:256
	global_load_dwordx4 v[172:175], v246, s[58:59] offset:256
	s_waitcnt vmcnt(12)
	v_mov_b32_e32 v226, v230
	v_pk_mul_f32 v[80:81], v[80:81], v[226:227] op_sel_hi:[1,0]
	v_pk_mul_f32 v[82:83], v[82:83], v[226:227] op_sel_hi:[1,0]
	v_pk_mul_f32 v[84:85], v[84:85], v[226:227] op_sel_hi:[1,0]
	v_pk_mul_f32 v[86:87], v[86:87], v[226:227] op_sel_hi:[1,0]
	v_pk_mul_f32 v[88:89], v[88:89], v[226:227] op_sel_hi:[1,0]
	v_pk_mul_f32 v[90:91], v[90:91], v[226:227] op_sel_hi:[1,0]
	v_pk_mul_f32 v[92:93], v[92:93], v[226:227] op_sel_hi:[1,0]
	v_pk_mul_f32 v[94:95], v[94:95], v[226:227] op_sel_hi:[1,0]
	v_pk_mul_f32 v[80:81], v[80:81], v[248:249] op_sel_hi:[1,0]
	v_pk_mul_f32 v[82:83], v[82:83], v[248:249] op_sel_hi:[1,0]
	v_pk_mul_f32 v[84:85], v[84:85], v[248:249] op_sel_hi:[1,0]
	v_pk_mul_f32 v[86:87], v[86:87], v[248:249] op_sel_hi:[1,0]
	v_pk_mul_f32 v[88:89], v[88:89], v[248:249] op_sel_hi:[1,0]
	v_pk_mul_f32 v[90:91], v[90:91], v[248:249] op_sel_hi:[1,0]
	v_pk_mul_f32 v[92:93], v[92:93], v[248:249] op_sel_hi:[1,0]
	v_pk_mul_f32 v[94:95], v[94:95], v[248:249] op_sel_hi:[1,0]
	v_exp_f32_e32 v80, v80
	v_exp_f32_e32 v81, v81
	v_exp_f32_e32 v82, v82
	v_exp_f32_e32 v83, v83
	v_exp_f32_e32 v84, v84
	v_exp_f32_e32 v85, v85
	v_exp_f32_e32 v86, v86
	v_exp_f32_e32 v87, v87
	v_exp_f32_e32 v88, v88
	v_exp_f32_e32 v89, v89
	v_exp_f32_e32 v90, v90
	v_exp_f32_e32 v91, v91
	v_exp_f32_e32 v92, v92
	v_exp_f32_e32 v93, v93
	v_exp_f32_e32 v94, v94
	v_exp_f32_e32 v95, v95
	v_pk_add_f32 v[80:81], v[80:81], 1.0 op_sel_hi:[1,0]
	v_pk_add_f32 v[82:83], v[82:83], 1.0 op_sel_hi:[1,0]
	v_pk_add_f32 v[84:85], v[84:85], 1.0 op_sel_hi:[1,0]
	v_pk_add_f32 v[86:87], v[86:87], 1.0 op_sel_hi:[1,0]
	v_pk_add_f32 v[88:89], v[88:89], 1.0 op_sel_hi:[1,0]
	v_pk_add_f32 v[90:91], v[90:91], 1.0 op_sel_hi:[1,0]
	v_pk_add_f32 v[92:93], v[92:93], 1.0 op_sel_hi:[1,0]
	v_pk_add_f32 v[94:95], v[94:95], 1.0 op_sel_hi:[1,0]
	v_rcp_f32_e32 v80, v80
	v_rcp_f32_e32 v81, v81
	v_rcp_f32_e32 v82, v82
	v_rcp_f32_e32 v83, v83
	v_rcp_f32_e32 v84, v84
	v_rcp_f32_e32 v85, v85
	v_rcp_f32_e32 v86, v86
	v_rcp_f32_e32 v87, v87
	v_rcp_f32_e32 v88, v88
	v_rcp_f32_e32 v89, v89
	v_rcp_f32_e32 v90, v90
	v_rcp_f32_e32 v91, v91
	v_rcp_f32_e32 v92, v92
	v_rcp_f32_e32 v93, v93
	v_rcp_f32_e32 v94, v94
	v_rcp_f32_e32 v95, v95
	v_lshlrev_b32_e32 v216, 16, v176
	v_and_b32_e32 v217, 0xffff0000, v176
	v_lshlrev_b32_e32 v236, 16, v180
	v_and_b32_e32 v237, 0xffff0000, v180
	v_lshlrev_b32_e32 v218, 16, v177
	v_and_b32_e32 v219, 0xffff0000, v177
	v_lshlrev_b32_e32 v238, 16, v181
	v_and_b32_e32 v239, 0xffff0000, v181
	v_lshlrev_b32_e32 v220, 16, v178
	v_and_b32_e32 v221, 0xffff0000, v178
	v_lshlrev_b32_e32 v240, 16, v182
	v_and_b32_e32 v241, 0xffff0000, v182
	v_lshlrev_b32_e32 v222, 16, v179
	v_and_b32_e32 v223, 0xffff0000, v179
	v_lshlrev_b32_e32 v242, 16, v183
	v_and_b32_e32 v243, 0xffff0000, v183
	v_pk_fma_f32 v[92:93], v[92:93], v[236:237], v[216:217]
	v_pk_fma_f32 v[94:95], v[94:95], v[238:239], v[218:219]
	v_pk_fma_f32 v[88:89], v[88:89], v[240:241], v[220:221]
	v_pk_fma_f32 v[90:91], v[90:91], v[242:243], v[222:223]
	v_pk_mul_f32 v[252:253], v[92:93], v[92:93]
	v_pk_fma_f32 v[252:253], v[94:95], v[94:95], v[252:253]
	v_pk_fma_f32 v[252:253], v[88:89], v[88:89], v[252:253]
	v_pk_fma_f32 v[252:253], v[90:91], v[90:91], v[252:253]
	v_lshlrev_b32_e32 v216, 16, v184
	v_and_b32_e32 v217, 0xffff0000, v184
	v_lshlrev_b32_e32 v236, 16, v196
	v_and_b32_e32 v237, 0xffff0000, v196
	v_lshlrev_b32_e32 v218, 16, v185
	v_and_b32_e32 v219, 0xffff0000, v185
	v_lshlrev_b32_e32 v238, 16, v197
	v_and_b32_e32 v239, 0xffff0000, v197
	v_lshlrev_b32_e32 v220, 16, v186
	v_and_b32_e32 v221, 0xffff0000, v186
	v_lshlrev_b32_e32 v240, 16, v198
	v_and_b32_e32 v241, 0xffff0000, v198
	v_lshlrev_b32_e32 v222, 16, v187
	v_and_b32_e32 v223, 0xffff0000, v187
	v_lshlrev_b32_e32 v242, 16, v199
	v_and_b32_e32 v243, 0xffff0000, v199
	v_pk_fma_f32 v[84:85], v[84:85], v[236:237], v[216:217]
	v_pk_fma_f32 v[86:87], v[86:87], v[238:239], v[218:219]
	v_pk_fma_f32 v[80:81], v[80:81], v[240:241], v[220:221]
	v_pk_fma_f32 v[82:83], v[82:83], v[242:243], v[222:223]
	v_pk_fma_f32 v[252:253], v[84:85], v[84:85], v[252:253]
	v_pk_fma_f32 v[252:253], v[86:87], v[86:87], v[252:253]
	v_pk_fma_f32 v[252:253], v[80:81], v[80:81], v[252:253]
	v_pk_fma_f32 v[252:253], v[82:83], v[82:83], v[252:253]
	v_add_f32_e32 v230, v252, v253
	v_add_u32_e32 v246, 0xa0000, v245
	global_load_dwordx4 v[176:179], v246, s[52:53]
	global_load_dwordx4 v[180:183], v246, s[58:59]
	global_load_dwordx4 v[184:187], v246, s[52:53] offset:256
	global_load_dwordx4 v[196:199], v246, s[58:59] offset:256
	s_waitcnt vmcnt(12)
	v_mov_b32_e32 v226, v231
	v_pk_mul_f32 v[64:65], v[64:65], v[226:227] op_sel_hi:[1,0]
	v_pk_mul_f32 v[66:67], v[66:67], v[226:227] op_sel_hi:[1,0]
	v_pk_mul_f32 v[68:69], v[68:69], v[226:227] op_sel_hi:[1,0]
	v_pk_mul_f32 v[70:71], v[70:71], v[226:227] op_sel_hi:[1,0]
	v_pk_mul_f32 v[72:73], v[72:73], v[226:227] op_sel_hi:[1,0]
	v_pk_mul_f32 v[74:75], v[74:75], v[226:227] op_sel_hi:[1,0]
	v_pk_mul_f32 v[76:77], v[76:77], v[226:227] op_sel_hi:[1,0]
	v_pk_mul_f32 v[78:79], v[78:79], v[226:227] op_sel_hi:[1,0]
	v_pk_mul_f32 v[64:65], v[64:65], v[248:249] op_sel_hi:[1,0]
	v_pk_mul_f32 v[66:67], v[66:67], v[248:249] op_sel_hi:[1,0]
	v_pk_mul_f32 v[68:69], v[68:69], v[248:249] op_sel_hi:[1,0]
	v_pk_mul_f32 v[70:71], v[70:71], v[248:249] op_sel_hi:[1,0]
	v_pk_mul_f32 v[72:73], v[72:73], v[248:249] op_sel_hi:[1,0]
	v_pk_mul_f32 v[74:75], v[74:75], v[248:249] op_sel_hi:[1,0]
	v_pk_mul_f32 v[76:77], v[76:77], v[248:249] op_sel_hi:[1,0]
	v_pk_mul_f32 v[78:79], v[78:79], v[248:249] op_sel_hi:[1,0]
	v_exp_f32_e32 v64, v64
	v_exp_f32_e32 v65, v65
	v_exp_f32_e32 v66, v66
	v_exp_f32_e32 v67, v67
	v_exp_f32_e32 v68, v68
	v_exp_f32_e32 v69, v69
	v_exp_f32_e32 v70, v70
	v_exp_f32_e32 v71, v71
	v_exp_f32_e32 v72, v72
	v_exp_f32_e32 v73, v73
	v_exp_f32_e32 v74, v74
	v_exp_f32_e32 v75, v75
	v_exp_f32_e32 v76, v76
	v_exp_f32_e32 v77, v77
	v_exp_f32_e32 v78, v78
	v_exp_f32_e32 v79, v79
	v_pk_add_f32 v[64:65], v[64:65], 1.0 op_sel_hi:[1,0]
	v_pk_add_f32 v[66:67], v[66:67], 1.0 op_sel_hi:[1,0]
	v_pk_add_f32 v[68:69], v[68:69], 1.0 op_sel_hi:[1,0]
	v_pk_add_f32 v[70:71], v[70:71], 1.0 op_sel_hi:[1,0]
	v_pk_add_f32 v[72:73], v[72:73], 1.0 op_sel_hi:[1,0]
	v_pk_add_f32 v[74:75], v[74:75], 1.0 op_sel_hi:[1,0]
	v_pk_add_f32 v[76:77], v[76:77], 1.0 op_sel_hi:[1,0]
	v_pk_add_f32 v[78:79], v[78:79], 1.0 op_sel_hi:[1,0]
	v_rcp_f32_e32 v64, v64
	v_rcp_f32_e32 v65, v65
	v_rcp_f32_e32 v66, v66
	v_rcp_f32_e32 v67, v67
	v_rcp_f32_e32 v68, v68
	v_rcp_f32_e32 v69, v69
	v_rcp_f32_e32 v70, v70
	v_rcp_f32_e32 v71, v71
	v_rcp_f32_e32 v72, v72
	v_rcp_f32_e32 v73, v73
	v_rcp_f32_e32 v74, v74
	v_rcp_f32_e32 v75, v75
	v_rcp_f32_e32 v76, v76
	v_rcp_f32_e32 v77, v77
	v_rcp_f32_e32 v78, v78
	v_rcp_f32_e32 v79, v79
	v_lshlrev_b32_e32 v216, 16, v200
	v_and_b32_e32 v217, 0xffff0000, v200
	v_lshlrev_b32_e32 v236, 16, v204
	v_and_b32_e32 v237, 0xffff0000, v204
	v_lshlrev_b32_e32 v218, 16, v201
	v_and_b32_e32 v219, 0xffff0000, v201
	v_lshlrev_b32_e32 v238, 16, v205
	v_and_b32_e32 v239, 0xffff0000, v205
	v_lshlrev_b32_e32 v220, 16, v202
	v_and_b32_e32 v221, 0xffff0000, v202
	v_lshlrev_b32_e32 v240, 16, v206
	v_and_b32_e32 v241, 0xffff0000, v206
	v_lshlrev_b32_e32 v222, 16, v203
	v_and_b32_e32 v223, 0xffff0000, v203
	v_lshlrev_b32_e32 v242, 16, v207
	v_and_b32_e32 v243, 0xffff0000, v207
	v_pk_fma_f32 v[76:77], v[76:77], v[236:237], v[216:217]
	v_pk_fma_f32 v[78:79], v[78:79], v[238:239], v[218:219]
	v_pk_fma_f32 v[72:73], v[72:73], v[240:241], v[220:221]
	v_pk_fma_f32 v[74:75], v[74:75], v[242:243], v[222:223]
	v_pk_mul_f32 v[252:253], v[76:77], v[76:77]
	v_pk_fma_f32 v[252:253], v[78:79], v[78:79], v[252:253]
	v_pk_fma_f32 v[252:253], v[72:73], v[72:73], v[252:253]
	v_pk_fma_f32 v[252:253], v[74:75], v[74:75], v[252:253]
	v_lshlrev_b32_e32 v216, 16, v208
	v_and_b32_e32 v217, 0xffff0000, v208
	v_lshlrev_b32_e32 v236, 16, v212
	v_and_b32_e32 v237, 0xffff0000, v212
	v_lshlrev_b32_e32 v218, 16, v209
	v_and_b32_e32 v219, 0xffff0000, v209
	v_lshlrev_b32_e32 v238, 16, v213
	v_and_b32_e32 v239, 0xffff0000, v213
	v_lshlrev_b32_e32 v220, 16, v210
	v_and_b32_e32 v221, 0xffff0000, v210
	v_lshlrev_b32_e32 v240, 16, v214
	v_and_b32_e32 v241, 0xffff0000, v214
	v_lshlrev_b32_e32 v222, 16, v211
	v_and_b32_e32 v223, 0xffff0000, v211
	v_lshlrev_b32_e32 v242, 16, v215
	v_and_b32_e32 v243, 0xffff0000, v215
	v_pk_fma_f32 v[68:69], v[68:69], v[236:237], v[216:217]
	v_pk_fma_f32 v[70:71], v[70:71], v[238:239], v[218:219]
	v_pk_fma_f32 v[64:65], v[64:65], v[240:241], v[220:221]
	v_pk_fma_f32 v[66:67], v[66:67], v[242:243], v[222:223]
	v_pk_fma_f32 v[252:253], v[68:69], v[68:69], v[252:253]
	v_pk_fma_f32 v[252:253], v[70:71], v[70:71], v[252:253]
	v_pk_fma_f32 v[252:253], v[64:65], v[64:65], v[252:253]
	v_pk_fma_f32 v[252:253], v[66:67], v[66:67], v[252:253]
	v_add_f32_e32 v231, v252, v253
	v_add_u32_e32 v246, 0xb0000, v245
	global_load_dwordx4 v[200:203], v246, s[52:53]
	global_load_dwordx4 v[204:207], v246, s[58:59]
	global_load_dwordx4 v[208:211], v246, s[52:53] offset:256
	global_load_dwordx4 v[212:215], v246, s[58:59] offset:256
	s_waitcnt vmcnt(12)
	v_mov_b32_e32 v226, v232
	v_pk_mul_f32 v[48:49], v[48:49], v[226:227] op_sel_hi:[1,0]
	v_pk_mul_f32 v[50:51], v[50:51], v[226:227] op_sel_hi:[1,0]
	v_pk_mul_f32 v[52:53], v[52:53], v[226:227] op_sel_hi:[1,0]
	v_pk_mul_f32 v[54:55], v[54:55], v[226:227] op_sel_hi:[1,0]
	v_pk_mul_f32 v[56:57], v[56:57], v[226:227] op_sel_hi:[1,0]
	v_pk_mul_f32 v[58:59], v[58:59], v[226:227] op_sel_hi:[1,0]
	v_pk_mul_f32 v[60:61], v[60:61], v[226:227] op_sel_hi:[1,0]
	v_pk_mul_f32 v[62:63], v[62:63], v[226:227] op_sel_hi:[1,0]
	v_pk_mul_f32 v[48:49], v[48:49], v[248:249] op_sel_hi:[1,0]
	v_pk_mul_f32 v[50:51], v[50:51], v[248:249] op_sel_hi:[1,0]
	v_pk_mul_f32 v[52:53], v[52:53], v[248:249] op_sel_hi:[1,0]
	v_pk_mul_f32 v[54:55], v[54:55], v[248:249] op_sel_hi:[1,0]
	v_pk_mul_f32 v[56:57], v[56:57], v[248:249] op_sel_hi:[1,0]
	v_pk_mul_f32 v[58:59], v[58:59], v[248:249] op_sel_hi:[1,0]
	v_pk_mul_f32 v[60:61], v[60:61], v[248:249] op_sel_hi:[1,0]
	v_pk_mul_f32 v[62:63], v[62:63], v[248:249] op_sel_hi:[1,0]
	v_exp_f32_e32 v48, v48
	v_exp_f32_e32 v49, v49
	v_exp_f32_e32 v50, v50
	v_exp_f32_e32 v51, v51
	v_exp_f32_e32 v52, v52
	v_exp_f32_e32 v53, v53
	v_exp_f32_e32 v54, v54
	v_exp_f32_e32 v55, v55
	v_exp_f32_e32 v56, v56
	v_exp_f32_e32 v57, v57
	v_exp_f32_e32 v58, v58
	v_exp_f32_e32 v59, v59
	v_exp_f32_e32 v60, v60
	v_exp_f32_e32 v61, v61
	v_exp_f32_e32 v62, v62
	v_exp_f32_e32 v63, v63
	v_pk_add_f32 v[48:49], v[48:49], 1.0 op_sel_hi:[1,0]
	v_pk_add_f32 v[50:51], v[50:51], 1.0 op_sel_hi:[1,0]
	v_pk_add_f32 v[52:53], v[52:53], 1.0 op_sel_hi:[1,0]
	v_pk_add_f32 v[54:55], v[54:55], 1.0 op_sel_hi:[1,0]
	v_pk_add_f32 v[56:57], v[56:57], 1.0 op_sel_hi:[1,0]
	v_pk_add_f32 v[58:59], v[58:59], 1.0 op_sel_hi:[1,0]
	v_pk_add_f32 v[60:61], v[60:61], 1.0 op_sel_hi:[1,0]
	v_pk_add_f32 v[62:63], v[62:63], 1.0 op_sel_hi:[1,0]
	v_rcp_f32_e32 v48, v48
	v_rcp_f32_e32 v49, v49
	v_rcp_f32_e32 v50, v50
	v_rcp_f32_e32 v51, v51
	v_rcp_f32_e32 v52, v52
	v_rcp_f32_e32 v53, v53
	v_rcp_f32_e32 v54, v54
	v_rcp_f32_e32 v55, v55
	v_rcp_f32_e32 v56, v56
	v_rcp_f32_e32 v57, v57
	v_rcp_f32_e32 v58, v58
	v_rcp_f32_e32 v59, v59
	v_rcp_f32_e32 v60, v60
	v_rcp_f32_e32 v61, v61
	v_rcp_f32_e32 v62, v62
	v_rcp_f32_e32 v63, v63
	v_lshlrev_b32_e32 v216, 16, v144
	v_and_b32_e32 v217, 0xffff0000, v144
	v_lshlrev_b32_e32 v236, 16, v148
	v_and_b32_e32 v237, 0xffff0000, v148
	v_lshlrev_b32_e32 v218, 16, v145
	v_and_b32_e32 v219, 0xffff0000, v145
	v_lshlrev_b32_e32 v238, 16, v149
	v_and_b32_e32 v239, 0xffff0000, v149
	v_lshlrev_b32_e32 v220, 16, v146
	v_and_b32_e32 v221, 0xffff0000, v146
	v_lshlrev_b32_e32 v240, 16, v150
	v_and_b32_e32 v241, 0xffff0000, v150
	v_lshlrev_b32_e32 v222, 16, v147
	v_and_b32_e32 v223, 0xffff0000, v147
	v_lshlrev_b32_e32 v242, 16, v151
	v_and_b32_e32 v243, 0xffff0000, v151
	v_pk_fma_f32 v[60:61], v[60:61], v[236:237], v[216:217]
	v_pk_fma_f32 v[62:63], v[62:63], v[238:239], v[218:219]
	v_pk_fma_f32 v[56:57], v[56:57], v[240:241], v[220:221]
	v_pk_fma_f32 v[58:59], v[58:59], v[242:243], v[222:223]
	v_pk_mul_f32 v[252:253], v[60:61], v[60:61]
	v_pk_fma_f32 v[252:253], v[62:63], v[62:63], v[252:253]
	v_pk_fma_f32 v[252:253], v[56:57], v[56:57], v[252:253]
	v_pk_fma_f32 v[252:253], v[58:59], v[58:59], v[252:253]
	v_lshlrev_b32_e32 v216, 16, v152
	v_and_b32_e32 v217, 0xffff0000, v152
	v_lshlrev_b32_e32 v236, 16, v156
	v_and_b32_e32 v237, 0xffff0000, v156
	v_lshlrev_b32_e32 v218, 16, v153
	v_and_b32_e32 v219, 0xffff0000, v153
	v_lshlrev_b32_e32 v238, 16, v157
	v_and_b32_e32 v239, 0xffff0000, v157
	v_lshlrev_b32_e32 v220, 16, v154
	v_and_b32_e32 v221, 0xffff0000, v154
	v_lshlrev_b32_e32 v240, 16, v158
	v_and_b32_e32 v241, 0xffff0000, v158
	v_lshlrev_b32_e32 v222, 16, v155
	v_and_b32_e32 v223, 0xffff0000, v155
	v_lshlrev_b32_e32 v242, 16, v159
	v_and_b32_e32 v243, 0xffff0000, v159
	v_pk_fma_f32 v[52:53], v[52:53], v[236:237], v[216:217]
	v_pk_fma_f32 v[54:55], v[54:55], v[238:239], v[218:219]
	v_pk_fma_f32 v[48:49], v[48:49], v[240:241], v[220:221]
	v_pk_fma_f32 v[50:51], v[50:51], v[242:243], v[222:223]
	v_pk_fma_f32 v[252:253], v[52:53], v[52:53], v[252:253]
	v_pk_fma_f32 v[252:253], v[54:55], v[54:55], v[252:253]
	v_pk_fma_f32 v[252:253], v[48:49], v[48:49], v[252:253]
	v_pk_fma_f32 v[252:253], v[50:51], v[50:51], v[252:253]
	v_add_f32_e32 v232, v252, v253
	s_waitcnt vmcnt(8)
	v_mov_b32_e32 v226, v233
	v_pk_mul_f32 v[32:33], v[32:33], v[226:227] op_sel_hi:[1,0]
	v_pk_mul_f32 v[34:35], v[34:35], v[226:227] op_sel_hi:[1,0]
	v_pk_mul_f32 v[36:37], v[36:37], v[226:227] op_sel_hi:[1,0]
	v_pk_mul_f32 v[38:39], v[38:39], v[226:227] op_sel_hi:[1,0]
	v_pk_mul_f32 v[40:41], v[40:41], v[226:227] op_sel_hi:[1,0]
	v_pk_mul_f32 v[42:43], v[42:43], v[226:227] op_sel_hi:[1,0]
	v_pk_mul_f32 v[44:45], v[44:45], v[226:227] op_sel_hi:[1,0]
	v_pk_mul_f32 v[46:47], v[46:47], v[226:227] op_sel_hi:[1,0]
	v_pk_mul_f32 v[32:33], v[32:33], v[248:249] op_sel_hi:[1,0]
	v_pk_mul_f32 v[34:35], v[34:35], v[248:249] op_sel_hi:[1,0]
	v_pk_mul_f32 v[36:37], v[36:37], v[248:249] op_sel_hi:[1,0]
	v_pk_mul_f32 v[38:39], v[38:39], v[248:249] op_sel_hi:[1,0]
	v_pk_mul_f32 v[40:41], v[40:41], v[248:249] op_sel_hi:[1,0]
	v_pk_mul_f32 v[42:43], v[42:43], v[248:249] op_sel_hi:[1,0]
	v_pk_mul_f32 v[44:45], v[44:45], v[248:249] op_sel_hi:[1,0]
	v_pk_mul_f32 v[46:47], v[46:47], v[248:249] op_sel_hi:[1,0]
	v_exp_f32_e32 v32, v32
	v_exp_f32_e32 v33, v33
	v_exp_f32_e32 v34, v34
	v_exp_f32_e32 v35, v35
	v_exp_f32_e32 v36, v36
	v_exp_f32_e32 v37, v37
	v_exp_f32_e32 v38, v38
	v_exp_f32_e32 v39, v39
	v_exp_f32_e32 v40, v40
	v_exp_f32_e32 v41, v41
	v_exp_f32_e32 v42, v42
	v_exp_f32_e32 v43, v43
	v_exp_f32_e32 v44, v44
	v_exp_f32_e32 v45, v45
	v_exp_f32_e32 v46, v46
	v_exp_f32_e32 v47, v47
	v_pk_add_f32 v[32:33], v[32:33], 1.0 op_sel_hi:[1,0]
	v_pk_add_f32 v[34:35], v[34:35], 1.0 op_sel_hi:[1,0]
	v_pk_add_f32 v[36:37], v[36:37], 1.0 op_sel_hi:[1,0]
	v_pk_add_f32 v[38:39], v[38:39], 1.0 op_sel_hi:[1,0]
	v_pk_add_f32 v[40:41], v[40:41], 1.0 op_sel_hi:[1,0]
	v_pk_add_f32 v[42:43], v[42:43], 1.0 op_sel_hi:[1,0]
	v_pk_add_f32 v[44:45], v[44:45], 1.0 op_sel_hi:[1,0]
	v_pk_add_f32 v[46:47], v[46:47], 1.0 op_sel_hi:[1,0]
	v_rcp_f32_e32 v32, v32
	v_rcp_f32_e32 v33, v33
	v_rcp_f32_e32 v34, v34
	v_rcp_f32_e32 v35, v35
	v_rcp_f32_e32 v36, v36
	v_rcp_f32_e32 v37, v37
	v_rcp_f32_e32 v38, v38
	v_rcp_f32_e32 v39, v39
	v_rcp_f32_e32 v40, v40
	v_rcp_f32_e32 v41, v41
	v_rcp_f32_e32 v42, v42
	v_rcp_f32_e32 v43, v43
	v_rcp_f32_e32 v44, v44
	v_rcp_f32_e32 v45, v45
	v_rcp_f32_e32 v46, v46
	v_rcp_f32_e32 v47, v47
	v_lshlrev_b32_e32 v216, 16, v160
	v_and_b32_e32 v217, 0xffff0000, v160
	v_lshlrev_b32_e32 v236, 16, v164
	v_and_b32_e32 v237, 0xffff0000, v164
	v_lshlrev_b32_e32 v218, 16, v161
	v_and_b32_e32 v219, 0xffff0000, v161
	v_lshlrev_b32_e32 v238, 16, v165
	v_and_b32_e32 v239, 0xffff0000, v165
	v_lshlrev_b32_e32 v220, 16, v162
	v_and_b32_e32 v221, 0xffff0000, v162
	v_lshlrev_b32_e32 v240, 16, v166
	v_and_b32_e32 v241, 0xffff0000, v166
	v_lshlrev_b32_e32 v222, 16, v163
	v_and_b32_e32 v223, 0xffff0000, v163
	v_lshlrev_b32_e32 v242, 16, v167
	v_and_b32_e32 v243, 0xffff0000, v167
	v_pk_fma_f32 v[44:45], v[44:45], v[236:237], v[216:217]
	v_pk_fma_f32 v[46:47], v[46:47], v[238:239], v[218:219]
	v_pk_fma_f32 v[40:41], v[40:41], v[240:241], v[220:221]
	v_pk_fma_f32 v[42:43], v[42:43], v[242:243], v[222:223]
	v_pk_mul_f32 v[252:253], v[44:45], v[44:45]
	v_pk_fma_f32 v[252:253], v[46:47], v[46:47], v[252:253]
	v_pk_fma_f32 v[252:253], v[40:41], v[40:41], v[252:253]
	v_pk_fma_f32 v[252:253], v[42:43], v[42:43], v[252:253]
	v_lshlrev_b32_e32 v216, 16, v168
	v_and_b32_e32 v217, 0xffff0000, v168
	v_lshlrev_b32_e32 v236, 16, v172
	v_and_b32_e32 v237, 0xffff0000, v172
	v_lshlrev_b32_e32 v218, 16, v169
	v_and_b32_e32 v219, 0xffff0000, v169
	v_lshlrev_b32_e32 v238, 16, v173
	v_and_b32_e32 v239, 0xffff0000, v173
	v_lshlrev_b32_e32 v220, 16, v170
	v_and_b32_e32 v221, 0xffff0000, v170
	v_lshlrev_b32_e32 v240, 16, v174
	v_and_b32_e32 v241, 0xffff0000, v174
	v_lshlrev_b32_e32 v222, 16, v171
	v_and_b32_e32 v223, 0xffff0000, v171
	v_lshlrev_b32_e32 v242, 16, v175
	v_and_b32_e32 v243, 0xffff0000, v175
	v_pk_fma_f32 v[36:37], v[36:37], v[236:237], v[216:217]
	v_pk_fma_f32 v[38:39], v[38:39], v[238:239], v[218:219]
	v_pk_fma_f32 v[32:33], v[32:33], v[240:241], v[220:221]
	v_pk_fma_f32 v[34:35], v[34:35], v[242:243], v[222:223]
	v_pk_fma_f32 v[252:253], v[36:37], v[36:37], v[252:253]
	v_pk_fma_f32 v[252:253], v[38:39], v[38:39], v[252:253]
	v_pk_fma_f32 v[252:253], v[32:33], v[32:33], v[252:253]
	v_pk_fma_f32 v[252:253], v[34:35], v[34:35], v[252:253]
	v_add_f32_e32 v233, v252, v253
	s_waitcnt vmcnt(4)
	v_mov_b32_e32 v226, v234
	v_pk_mul_f32 v[16:17], v[16:17], v[226:227] op_sel_hi:[1,0]
	v_pk_mul_f32 v[18:19], v[18:19], v[226:227] op_sel_hi:[1,0]
	v_pk_mul_f32 v[20:21], v[20:21], v[226:227] op_sel_hi:[1,0]
	v_pk_mul_f32 v[22:23], v[22:23], v[226:227] op_sel_hi:[1,0]
	v_pk_mul_f32 v[24:25], v[24:25], v[226:227] op_sel_hi:[1,0]
	v_pk_mul_f32 v[26:27], v[26:27], v[226:227] op_sel_hi:[1,0]
	v_pk_mul_f32 v[28:29], v[28:29], v[226:227] op_sel_hi:[1,0]
	v_pk_mul_f32 v[30:31], v[30:31], v[226:227] op_sel_hi:[1,0]
	v_pk_mul_f32 v[16:17], v[16:17], v[248:249] op_sel_hi:[1,0]
	v_pk_mul_f32 v[18:19], v[18:19], v[248:249] op_sel_hi:[1,0]
	v_pk_mul_f32 v[20:21], v[20:21], v[248:249] op_sel_hi:[1,0]
	v_pk_mul_f32 v[22:23], v[22:23], v[248:249] op_sel_hi:[1,0]
	v_pk_mul_f32 v[24:25], v[24:25], v[248:249] op_sel_hi:[1,0]
	v_pk_mul_f32 v[26:27], v[26:27], v[248:249] op_sel_hi:[1,0]
	v_pk_mul_f32 v[28:29], v[28:29], v[248:249] op_sel_hi:[1,0]
	v_pk_mul_f32 v[30:31], v[30:31], v[248:249] op_sel_hi:[1,0]
	v_exp_f32_e32 v16, v16
	v_exp_f32_e32 v17, v17
	v_exp_f32_e32 v18, v18
	v_exp_f32_e32 v19, v19
	v_exp_f32_e32 v20, v20
	v_exp_f32_e32 v21, v21
	v_exp_f32_e32 v22, v22
	v_exp_f32_e32 v23, v23
	v_exp_f32_e32 v24, v24
	v_exp_f32_e32 v25, v25
	v_exp_f32_e32 v26, v26
	v_exp_f32_e32 v27, v27
	v_exp_f32_e32 v28, v28
	v_exp_f32_e32 v29, v29
	v_exp_f32_e32 v30, v30
	v_exp_f32_e32 v31, v31
	v_pk_add_f32 v[16:17], v[16:17], 1.0 op_sel_hi:[1,0]
	v_pk_add_f32 v[18:19], v[18:19], 1.0 op_sel_hi:[1,0]
	v_pk_add_f32 v[20:21], v[20:21], 1.0 op_sel_hi:[1,0]
	v_pk_add_f32 v[22:23], v[22:23], 1.0 op_sel_hi:[1,0]
	v_pk_add_f32 v[24:25], v[24:25], 1.0 op_sel_hi:[1,0]
	v_pk_add_f32 v[26:27], v[26:27], 1.0 op_sel_hi:[1,0]
	v_pk_add_f32 v[28:29], v[28:29], 1.0 op_sel_hi:[1,0]
	v_pk_add_f32 v[30:31], v[30:31], 1.0 op_sel_hi:[1,0]
	v_rcp_f32_e32 v16, v16
	v_rcp_f32_e32 v17, v17
	v_rcp_f32_e32 v18, v18
	v_rcp_f32_e32 v19, v19
	v_rcp_f32_e32 v20, v20
	v_rcp_f32_e32 v21, v21
	v_rcp_f32_e32 v22, v22
	v_rcp_f32_e32 v23, v23
	v_rcp_f32_e32 v24, v24
	v_rcp_f32_e32 v25, v25
	v_rcp_f32_e32 v26, v26
	v_rcp_f32_e32 v27, v27
	v_rcp_f32_e32 v28, v28
	v_rcp_f32_e32 v29, v29
	v_rcp_f32_e32 v30, v30
	v_rcp_f32_e32 v31, v31
	v_lshlrev_b32_e32 v216, 16, v176
	v_and_b32_e32 v217, 0xffff0000, v176
	v_lshlrev_b32_e32 v236, 16, v180
	v_and_b32_e32 v237, 0xffff0000, v180
	v_lshlrev_b32_e32 v218, 16, v177
	v_and_b32_e32 v219, 0xffff0000, v177
	v_lshlrev_b32_e32 v238, 16, v181
	v_and_b32_e32 v239, 0xffff0000, v181
	v_lshlrev_b32_e32 v220, 16, v178
	v_and_b32_e32 v221, 0xffff0000, v178
	v_lshlrev_b32_e32 v240, 16, v182
	v_and_b32_e32 v241, 0xffff0000, v182
	v_lshlrev_b32_e32 v222, 16, v179
	v_and_b32_e32 v223, 0xffff0000, v179
	v_lshlrev_b32_e32 v242, 16, v183
	v_and_b32_e32 v243, 0xffff0000, v183
	v_pk_fma_f32 v[28:29], v[28:29], v[236:237], v[216:217]
	v_pk_fma_f32 v[30:31], v[30:31], v[238:239], v[218:219]
	v_pk_fma_f32 v[24:25], v[24:25], v[240:241], v[220:221]
	v_pk_fma_f32 v[26:27], v[26:27], v[242:243], v[222:223]
	v_pk_mul_f32 v[252:253], v[28:29], v[28:29]
	v_pk_fma_f32 v[252:253], v[30:31], v[30:31], v[252:253]
	v_pk_fma_f32 v[252:253], v[24:25], v[24:25], v[252:253]
	v_pk_fma_f32 v[252:253], v[26:27], v[26:27], v[252:253]
	v_lshlrev_b32_e32 v216, 16, v184
	v_and_b32_e32 v217, 0xffff0000, v184
	v_lshlrev_b32_e32 v236, 16, v196
	v_and_b32_e32 v237, 0xffff0000, v196
	v_lshlrev_b32_e32 v218, 16, v185
	v_and_b32_e32 v219, 0xffff0000, v185
	v_lshlrev_b32_e32 v238, 16, v197
	v_and_b32_e32 v239, 0xffff0000, v197
	v_lshlrev_b32_e32 v220, 16, v186
	v_and_b32_e32 v221, 0xffff0000, v186
	v_lshlrev_b32_e32 v240, 16, v198
	v_and_b32_e32 v241, 0xffff0000, v198
	v_lshlrev_b32_e32 v222, 16, v187
	v_and_b32_e32 v223, 0xffff0000, v187
	v_lshlrev_b32_e32 v242, 16, v199
	v_and_b32_e32 v243, 0xffff0000, v199
	v_pk_fma_f32 v[20:21], v[20:21], v[236:237], v[216:217]
	v_pk_fma_f32 v[22:23], v[22:23], v[238:239], v[218:219]
	v_pk_fma_f32 v[16:17], v[16:17], v[240:241], v[220:221]
	v_pk_fma_f32 v[18:19], v[18:19], v[242:243], v[222:223]
	v_pk_fma_f32 v[252:253], v[20:21], v[20:21], v[252:253]
	v_pk_fma_f32 v[252:253], v[22:23], v[22:23], v[252:253]
	v_pk_fma_f32 v[252:253], v[16:17], v[16:17], v[252:253]
	v_pk_fma_f32 v[252:253], v[18:19], v[18:19], v[252:253]
	v_add_f32_e32 v234, v252, v253
	s_waitcnt vmcnt(0)
	v_mov_b32_e32 v226, v235
	v_pk_mul_f32 v[0:1], v[0:1], v[226:227] op_sel_hi:[1,0]
	v_pk_mul_f32 v[2:3], v[2:3], v[226:227] op_sel_hi:[1,0]
	v_pk_mul_f32 v[4:5], v[4:5], v[226:227] op_sel_hi:[1,0]
	v_pk_mul_f32 v[6:7], v[6:7], v[226:227] op_sel_hi:[1,0]
	v_pk_mul_f32 v[8:9], v[8:9], v[226:227] op_sel_hi:[1,0]
	v_pk_mul_f32 v[10:11], v[10:11], v[226:227] op_sel_hi:[1,0]
	v_pk_mul_f32 v[12:13], v[12:13], v[226:227] op_sel_hi:[1,0]
	v_pk_mul_f32 v[14:15], v[14:15], v[226:227] op_sel_hi:[1,0]
	v_pk_mul_f32 v[0:1], v[0:1], v[248:249] op_sel_hi:[1,0]
	v_pk_mul_f32 v[2:3], v[2:3], v[248:249] op_sel_hi:[1,0]
	v_pk_mul_f32 v[4:5], v[4:5], v[248:249] op_sel_hi:[1,0]
	v_pk_mul_f32 v[6:7], v[6:7], v[248:249] op_sel_hi:[1,0]
	v_pk_mul_f32 v[8:9], v[8:9], v[248:249] op_sel_hi:[1,0]
	v_pk_mul_f32 v[10:11], v[10:11], v[248:249] op_sel_hi:[1,0]
	v_pk_mul_f32 v[12:13], v[12:13], v[248:249] op_sel_hi:[1,0]
	v_pk_mul_f32 v[14:15], v[14:15], v[248:249] op_sel_hi:[1,0]
	v_exp_f32_e32 v0, v0
	v_exp_f32_e32 v1, v1
	v_exp_f32_e32 v2, v2
	v_exp_f32_e32 v3, v3
	v_exp_f32_e32 v4, v4
	v_exp_f32_e32 v5, v5
	v_exp_f32_e32 v6, v6
	v_exp_f32_e32 v7, v7
	v_exp_f32_e32 v8, v8
	v_exp_f32_e32 v9, v9
	v_exp_f32_e32 v10, v10
	v_exp_f32_e32 v11, v11
	v_exp_f32_e32 v12, v12
	v_exp_f32_e32 v13, v13
	v_exp_f32_e32 v14, v14
	v_exp_f32_e32 v15, v15
	v_pk_add_f32 v[0:1], v[0:1], 1.0 op_sel_hi:[1,0]
	v_pk_add_f32 v[2:3], v[2:3], 1.0 op_sel_hi:[1,0]
	v_pk_add_f32 v[4:5], v[4:5], 1.0 op_sel_hi:[1,0]
	v_pk_add_f32 v[6:7], v[6:7], 1.0 op_sel_hi:[1,0]
	v_pk_add_f32 v[8:9], v[8:9], 1.0 op_sel_hi:[1,0]
	v_pk_add_f32 v[10:11], v[10:11], 1.0 op_sel_hi:[1,0]
	v_pk_add_f32 v[12:13], v[12:13], 1.0 op_sel_hi:[1,0]
	v_pk_add_f32 v[14:15], v[14:15], 1.0 op_sel_hi:[1,0]
	v_rcp_f32_e32 v0, v0
	v_rcp_f32_e32 v1, v1
	v_rcp_f32_e32 v2, v2
	v_rcp_f32_e32 v3, v3
	v_rcp_f32_e32 v4, v4
	v_rcp_f32_e32 v5, v5
	v_rcp_f32_e32 v6, v6
	v_rcp_f32_e32 v7, v7
	v_rcp_f32_e32 v8, v8
	v_rcp_f32_e32 v9, v9
	v_rcp_f32_e32 v10, v10
	v_rcp_f32_e32 v11, v11
	v_rcp_f32_e32 v12, v12
	v_rcp_f32_e32 v13, v13
	v_rcp_f32_e32 v14, v14
	v_rcp_f32_e32 v15, v15
	v_lshlrev_b32_e32 v216, 16, v200
	v_and_b32_e32 v217, 0xffff0000, v200
	v_lshlrev_b32_e32 v236, 16, v204
	v_and_b32_e32 v237, 0xffff0000, v204
	v_lshlrev_b32_e32 v218, 16, v201
	v_and_b32_e32 v219, 0xffff0000, v201
	v_lshlrev_b32_e32 v238, 16, v205
	v_and_b32_e32 v239, 0xffff0000, v205
	v_lshlrev_b32_e32 v220, 16, v202
	v_and_b32_e32 v221, 0xffff0000, v202
	v_lshlrev_b32_e32 v240, 16, v206
	v_and_b32_e32 v241, 0xffff0000, v206
	v_lshlrev_b32_e32 v222, 16, v203
	v_and_b32_e32 v223, 0xffff0000, v203
	v_lshlrev_b32_e32 v242, 16, v207
	v_and_b32_e32 v243, 0xffff0000, v207
	v_pk_fma_f32 v[12:13], v[12:13], v[236:237], v[216:217]
	v_pk_fma_f32 v[14:15], v[14:15], v[238:239], v[218:219]
	v_pk_fma_f32 v[8:9], v[8:9], v[240:241], v[220:221]
	v_pk_fma_f32 v[10:11], v[10:11], v[242:243], v[222:223]
	v_pk_mul_f32 v[252:253], v[12:13], v[12:13]
	v_pk_fma_f32 v[252:253], v[14:15], v[14:15], v[252:253]
	v_pk_fma_f32 v[252:253], v[8:9], v[8:9], v[252:253]
	v_pk_fma_f32 v[252:253], v[10:11], v[10:11], v[252:253]
	v_lshlrev_b32_e32 v216, 16, v208
	v_and_b32_e32 v217, 0xffff0000, v208
	v_lshlrev_b32_e32 v236, 16, v212
	v_and_b32_e32 v237, 0xffff0000, v212
	v_lshlrev_b32_e32 v218, 16, v209
	v_and_b32_e32 v219, 0xffff0000, v209
	v_lshlrev_b32_e32 v238, 16, v213
	v_and_b32_e32 v239, 0xffff0000, v213
	v_lshlrev_b32_e32 v220, 16, v210
	v_and_b32_e32 v221, 0xffff0000, v210
	v_lshlrev_b32_e32 v240, 16, v214
	v_and_b32_e32 v241, 0xffff0000, v214
	v_lshlrev_b32_e32 v222, 16, v211
	v_and_b32_e32 v223, 0xffff0000, v211
	v_lshlrev_b32_e32 v242, 16, v215
	v_and_b32_e32 v243, 0xffff0000, v215
	v_pk_fma_f32 v[4:5], v[4:5], v[236:237], v[216:217]
	v_pk_fma_f32 v[6:7], v[6:7], v[238:239], v[218:219]
	v_pk_fma_f32 v[0:1], v[0:1], v[240:241], v[220:221]
	v_pk_fma_f32 v[2:3], v[2:3], v[242:243], v[222:223]
	v_pk_fma_f32 v[252:253], v[4:5], v[4:5], v[252:253]
	v_pk_fma_f32 v[252:253], v[6:7], v[6:7], v[252:253]
	v_pk_fma_f32 v[252:253], v[0:1], v[0:1], v[252:253]
	v_pk_fma_f32 v[252:253], v[2:3], v[2:3], v[252:253]
	v_add_f32_e32 v235, v252, v253
	ds_bpermute_b32 v236, v251, v228
	ds_bpermute_b32 v237, v251, v229
	ds_bpermute_b32 v238, v251, v230
	ds_bpermute_b32 v239, v251, v231
	ds_bpermute_b32 v240, v251, v232
	ds_bpermute_b32 v241, v251, v233
	ds_bpermute_b32 v242, v251, v234
	ds_bpermute_b32 v243, v251, v235
	s_waitcnt lgkmcnt(0)
	v_add_f32_e32 v228, v228, v236
	v_add_f32_e32 v229, v229, v237
	v_add_f32_e32 v230, v230, v238
	v_add_f32_e32 v231, v231, v239
	v_add_f32_e32 v232, v232, v240
	v_add_f32_e32 v233, v233, v241
	v_add_f32_e32 v234, v234, v242
	v_add_f32_e32 v235, v235, v243
	ds_bpermute_b32 v236, v254, v228
	ds_bpermute_b32 v237, v254, v229
	ds_bpermute_b32 v238, v254, v230
	ds_bpermute_b32 v239, v254, v231
	ds_bpermute_b32 v240, v254, v232
	ds_bpermute_b32 v241, v254, v233
	ds_bpermute_b32 v242, v254, v234
	ds_bpermute_b32 v243, v254, v235
	s_waitcnt lgkmcnt(0)
	v_add_f32_e32 v228, v228, v236
	v_add_f32_e32 v229, v229, v237
	v_add_f32_e32 v230, v230, v238
	v_add_f32_e32 v231, v231, v239
	v_add_f32_e32 v232, v232, v240
	v_add_f32_e32 v233, v233, v241
	v_add_f32_e32 v234, v234, v242
	v_add_f32_e32 v235, v235, v243
	s_and_saveexec_b64 s[30:31], s[0:1]
	global_atomic_add_f32 v244, v228, s[16:17] offset:0
	global_atomic_add_f32 v244, v229, s[16:17] offset:64
	global_atomic_add_f32 v244, v230, s[16:17] offset:128
	global_atomic_add_f32 v244, v231, s[16:17] offset:192
	global_atomic_add_f32 v244, v232, s[16:17] offset:512
	global_atomic_add_f32 v244, v233, s[16:17] offset:576
	global_atomic_add_f32 v244, v234, s[16:17] offset:640
	global_atomic_add_f32 v244, v235, s[16:17] offset:704
	s_or_b64 exec, exec, s[30:31]
	s_lshl_b32 s8, s8, 6
	s_ashr_i32 s9, s8, 31
	s_waitcnt vmcnt(0)
	s_lshl_b64 s[8:9], s[8:9], 2
	s_add_u32 s8, s50, s8
	s_addc_u32 s9, s51, s9
	v_mov_b32_e32 v255, 1
	s_and_saveexec_b64 s[30:31], s[6:7]
	global_atomic_add v131, v255, s[8:9]
	s_or_b64 exec, exec, s[30:31]
	global_load_dwordx4 v[144:147], v247, s[10:11]
	global_load_dwordx4 v[148:151], v247, s[10:11] offset:16
	global_load_dwordx4 v[152:155], v247, s[10:11] offset:512
	global_load_dwordx4 v[156:159], v247, s[10:11] offset:528
	s_mov_b32 s23, 0x400001
.Lp8_poll:
	global_load_dword v255, v131, s[8:9] sc1
	s_waitcnt vmcnt(0)
	v_readfirstlane_b32 s25, v255
	s_cmp_gt_u32 s25, 63
	s_cbranch_scc1 .Lp8_arrived
	s_sleep 2
	s_add_i32 s23, s23, -1
	s_cmp_eq_u32 s23, 0
	s_cbranch_scc0 .Lp8_poll
.Lp8_arrived:
	global_load_dword v228, v244, s[16:17] offset:0 sc1
	global_load_dword v229, v244, s[16:17] offset:64 sc1
	global_load_dword v230, v244, s[16:17] offset:128 sc1
	global_load_dword v231, v244, s[16:17] offset:192 sc1
	global_load_dword v232, v244, s[16:17] offset:512 sc1
	global_load_dword v233, v244, s[16:17] offset:576 sc1
	global_load_dword v234, v244, s[16:17] offset:640 sc1
	global_load_dword v235, v244, s[16:17] offset:704 sc1
	v_lshlrev_b32_e32 v245, 1, v245
	s_waitcnt vmcnt(0)
	v_fmamk_f32 v228, v228, 0x3a000000, v195
	v_fmamk_f32 v229, v229, 0x3a000000, v195
	v_fmamk_f32 v230, v230, 0x3a000000, v195
	v_fmamk_f32 v231, v231, 0x3a000000, v195
	v_fmamk_f32 v232, v232, 0x3a000000, v195
	v_fmamk_f32 v233, v233, 0x3a000000, v195
	v_fmamk_f32 v234, v234, 0x3a000000, v195
	v_fmamk_f32 v235, v235, 0x3a000000, v195
	v_mul_f32_e32 v236, 0x4b800000, v228
	v_mul_f32_e32 v237, 0x4b800000, v229
	v_mul_f32_e32 v238, 0x4b800000, v230
	v_mul_f32_e32 v239, 0x4b800000, v231
	v_mul_f32_e32 v240, 0x4b800000, v232
	v_mul_f32_e32 v241, 0x4b800000, v233
	v_mul_f32_e32 v242, 0x4b800000, v234
	v_mul_f32_e32 v243, 0x4b800000, v235
	v_cmp_gt_f32_e32 vcc, s61, v228
	s_nop 1
	v_cndmask_b32_e32 v228, v228, v236, vcc
	v_cndmask_b32_e32 v236, 1.0, v249, vcc
	v_cmp_gt_f32_e32 vcc, s61, v229
	s_nop 1
	v_cndmask_b32_e32 v229, v229, v237, vcc
	v_cndmask_b32_e32 v237, 1.0, v249, vcc
	v_cmp_gt_f32_e32 vcc, s61, v230
	s_nop 1
	v_cndmask_b32_e32 v230, v230, v238, vcc
	v_cndmask_b32_e32 v238, 1.0, v249, vcc
	v_cmp_gt_f32_e32 vcc, s61, v231
	s_nop 1
	v_cndmask_b32_e32 v231, v231, v239, vcc
	v_cndmask_b32_e32 v239, 1.0, v249, vcc
	v_cmp_gt_f32_e32 vcc, s61, v232
	s_nop 1
	v_cndmask_b32_e32 v232, v232, v240, vcc
	v_cndmask_b32_e32 v240, 1.0, v249, vcc
	v_cmp_gt_f32_e32 vcc, s61, v233
	s_nop 1
	v_cndmask_b32_e32 v233, v233, v241, vcc
	v_cndmask_b32_e32 v241, 1.0, v249, vcc
	v_cmp_gt_f32_e32 vcc, s61, v234
	s_nop 1
	v_cndmask_b32_e32 v234, v234, v242, vcc
	v_cndmask_b32_e32 v242, 1.0, v249, vcc
	v_cmp_gt_f32_e32 vcc, s61, v235
	s_nop 1
	v_cndmask_b32_e32 v235, v235, v243, vcc
	v_cndmask_b32_e32 v243, 1.0, v249, vcc
	v_rsq_f32_e32 v228, v228
	v_rsq_f32_e32 v229, v229
	v_rsq_f32_e32 v230, v230
	v_rsq_f32_e32 v231, v231
	v_rsq_f32_e32 v232, v232
	v_rsq_f32_e32 v233, v233
	v_rsq_f32_e32 v234, v234
	v_rsq_f32_e32 v235, v235
	s_nop 0
	v_mul_f32_e32 v228, v228, v236
	v_mul_f32_e32 v229, v229, v237
	v_mul_f32_e32 v230, v230, v238
	v_mul_f32_e32 v231, v231, v239
	v_mul_f32_e32 v232, v232, v240
	v_mul_f32_e32 v233, v233, v241
	v_mul_f32_e32 v234, v234, v242
	v_mul_f32_e32 v235, v235, v243
	v_mov_b32_e32 v226, v228
	v_pk_mul_f32 v[112:113], v[112:113], v[226:227] op_sel_hi:[1,0]
	v_pk_mul_f32 v[114:115], v[114:115], v[226:227] op_sel_hi:[1,0]
	v_pk_mul_f32 v[116:117], v[116:117], v[226:227] op_sel_hi:[1,0]
	v_pk_mul_f32 v[118:119], v[118:119], v[226:227] op_sel_hi:[1,0]
	v_pk_mul_f32 v[120:121], v[120:121], v[226:227] op_sel_hi:[1,0]
	v_pk_mul_f32 v[122:123], v[122:123], v[226:227] op_sel_hi:[1,0]
	v_pk_mul_f32 v[124:125], v[124:125], v[226:227] op_sel_hi:[1,0]
	v_pk_mul_f32 v[126:127], v[126:127], v[226:227] op_sel_hi:[1,0]
	v_pk_mul_f32 v[124:125], v[144:145], v[124:125]
	v_pk_mul_f32 v[126:127], v[146:147], v[126:127]
	v_pk_mul_f32 v[120:121], v[148:149], v[120:121]
	v_pk_mul_f32 v[122:123], v[150:151], v[122:123]
	v_pk_mul_f32 v[116:117], v[152:153], v[116:117]
	v_pk_mul_f32 v[118:119], v[154:155], v[118:119]
	v_pk_mul_f32 v[112:113], v[156:157], v[112:113]
	v_pk_mul_f32 v[114:115], v[158:159], v[114:115]
	global_store_dwordx4 v245, v[124:127], s[48:49]
	global_store_dwordx4 v245, v[120:123], s[48:49] offset:16
	global_store_dwordx4 v245, v[116:119], s[48:49] offset:512
	global_store_dwordx4 v245, v[112:115], s[48:49] offset:528
	v_mov_b32_e32 v226, v229
	v_pk_mul_f32 v[96:97], v[96:97], v[226:227] op_sel_hi:[1,0]
	v_pk_mul_f32 v[98:99], v[98:99], v[226:227] op_sel_hi:[1,0]
	v_pk_mul_f32 v[100:101], v[100:101], v[226:227] op_sel_hi:[1,0]
	v_pk_mul_f32 v[102:103], v[102:103], v[226:227] op_sel_hi:[1,0]
	v_pk_mul_f32 v[104:105], v[104:105], v[226:227] op_sel_hi:[1,0]
	v_pk_mul_f32 v[106:107], v[106:107], v[226:227] op_sel_hi:[1,0]
	v_pk_mul_f32 v[108:109], v[108:109], v[226:227] op_sel_hi:[1,0]
	v_pk_mul_f32 v[110:111], v[110:111], v[226:227] op_sel_hi:[1,0]
	v_pk_mul_f32 v[108:109], v[144:145], v[108:109]
	v_pk_mul_f32 v[110:111], v[146:147], v[110:111]
	v_pk_mul_f32 v[104:105], v[148:149], v[104:105]
	v_pk_mul_f32 v[106:107], v[150:151], v[106:107]
	v_pk_mul_f32 v[100:101], v[152:153], v[100:101]
	v_pk_mul_f32 v[102:103], v[154:155], v[102:103]
	v_pk_mul_f32 v[96:97], v[156:157], v[96:97]
	v_pk_mul_f32 v[98:99], v[158:159], v[98:99]
	v_add_u32_e32 v246, 0x20000, v245
	global_store_dwordx4 v246, v[108:111], s[48:49]
	global_store_dwordx4 v246, v[104:107], s[48:49] offset:16
	global_store_dwordx4 v246, v[100:103], s[48:49] offset:512
	global_store_dwordx4 v246, v[96:99], s[48:49] offset:528
	v_mov_b32_e32 v226, v230
	v_pk_mul_f32 v[80:81], v[80:81], v[226:227] op_sel_hi:[1,0]
	v_pk_mul_f32 v[82:83], v[82:83], v[226:227] op_sel_hi:[1,0]
	v_pk_mul_f32 v[84:85], v[84:85], v[226:227] op_sel_hi:[1,0]
	v_pk_mul_f32 v[86:87], v[86:87], v[226:227] op_sel_hi:[1,0]
	v_pk_mul_f32 v[88:89], v[88:89], v[226:227] op_sel_hi:[1,0]
	v_pk_mul_f32 v[90:91], v[90:91], v[226:227] op_sel_hi:[1,0]
	v_pk_mul_f32 v[92:93], v[92:93], v[226:227] op_sel_hi:[1,0]
	v_pk_mul_f32 v[94:95], v[94:95], v[226:227] op_sel_hi:[1,0]
	v_pk_mul_f32 v[92:93], v[144:145], v[92:93]
	v_pk_mul_f32 v[94:95], v[146:147], v[94:95]
	v_pk_mul_f32 v[88:89], v[148:149], v[88:89]
	v_pk_mul_f32 v[90:91], v[150:151], v[90:91]
	v_pk_mul_f32 v[84:85], v[152:153], v[84:85]
	v_pk_mul_f32 v[86:87], v[154:155], v[86:87]
	v_pk_mul_f32 v[80:81], v[156:157], v[80:81]
	v_pk_mul_f32 v[82:83], v[158:159], v[82:83]
	v_add_u32_e32 v246, 0x40000, v245
	global_store_dwordx4 v246, v[92:95], s[48:49]
	global_store_dwordx4 v246, v[88:91], s[48:49] offset:16
	global_store_dwordx4 v246, v[84:87], s[48:49] offset:512
	global_store_dwordx4 v246, v[80:83], s[48:49] offset:528
	v_mov_b32_e32 v226, v231
	v_pk_mul_f32 v[64:65], v[64:65], v[226:227] op_sel_hi:[1,0]
	v_pk_mul_f32 v[66:67], v[66:67], v[226:227] op_sel_hi:[1,0]
	v_pk_mul_f32 v[68:69], v[68:69], v[226:227] op_sel_hi:[1,0]
	v_pk_mul_f32 v[70:71], v[70:71], v[226:227] op_sel_hi:[1,0]
	v_pk_mul_f32 v[72:73], v[72:73], v[226:227] op_sel_hi:[1,0]
	v_pk_mul_f32 v[74:75], v[74:75], v[226:227] op_sel_hi:[1,0]
	v_pk_mul_f32 v[76:77], v[76:77], v[226:227] op_sel_hi:[1,0]
	v_pk_mul_f32 v[78:79], v[78:79], v[226:227] op_sel_hi:[1,0]
	v_pk_mul_f32 v[76:77], v[144:145], v[76:77]
	v_pk_mul_f32 v[78:79], v[146:147], v[78:79]
	v_pk_mul_f32 v[72:73], v[148:149], v[72:73]
	v_pk_mul_f32 v[74:75], v[150:151], v[74:75]
	v_pk_mul_f32 v[68:69], v[152:153], v[68:69]
	v_pk_mul_f32 v[70:71], v[154:155], v[70:71]
	v_pk_mul_f32 v[64:65], v[156:157], v[64:65]
	v_pk_mul_f32 v[66:67], v[158:159], v[66:67]
	v_add_u32_e32 v246, 0x60000, v245
	global_store_dwordx4 v246, v[76:79], s[48:49]
	global_store_dwordx4 v246, v[72:75], s[48:49] offset:16
	global_store_dwordx4 v246, v[68:71], s[48:49] offset:512
	global_store_dwordx4 v246, v[64:67], s[48:49] offset:528
	v_mov_b32_e32 v226, v232
	v_pk_mul_f32 v[48:49], v[48:49], v[226:227] op_sel_hi:[1,0]
	v_pk_mul_f32 v[50:51], v[50:51], v[226:227] op_sel_hi:[1,0]
	v_pk_mul_f32 v[52:53], v[52:53], v[226:227] op_sel_hi:[1,0]
	v_pk_mul_f32 v[54:55], v[54:55], v[226:227] op_sel_hi:[1,0]
	v_pk_mul_f32 v[56:57], v[56:57], v[226:227] op_sel_hi:[1,0]
	v_pk_mul_f32 v[58:59], v[58:59], v[226:227] op_sel_hi:[1,0]
	v_pk_mul_f32 v[60:61], v[60:61], v[226:227] op_sel_hi:[1,0]
	v_pk_mul_f32 v[62:63], v[62:63], v[226:227] op_sel_hi:[1,0]
	v_pk_mul_f32 v[60:61], v[144:145], v[60:61]
	v_pk_mul_f32 v[62:63], v[146:147], v[62:63]
	v_pk_mul_f32 v[56:57], v[148:149], v[56:57]
	v_pk_mul_f32 v[58:59], v[150:151], v[58:59]
	v_pk_mul_f32 v[52:53], v[152:153], v[52:53]
	v_pk_mul_f32 v[54:55], v[154:155], v[54:55]
	v_pk_mul_f32 v[48:49], v[156:157], v[48:49]
	v_pk_mul_f32 v[50:51], v[158:159], v[50:51]
	v_add_u32_e32 v246, 0x100000, v245
	global_store_dwordx4 v246, v[60:63], s[48:49]
	global_store_dwordx4 v246, v[56:59], s[48:49] offset:16
	global_store_dwordx4 v246, v[52:55], s[48:49] offset:512
	global_store_dwordx4 v246, v[48:51], s[48:49] offset:528
	v_mov_b32_e32 v226, v233
	v_pk_mul_f32 v[32:33], v[32:33], v[226:227] op_sel_hi:[1,0]
	v_pk_mul_f32 v[34:35], v[34:35], v[226:227] op_sel_hi:[1,0]
	v_pk_mul_f32 v[36:37], v[36:37], v[226:227] op_sel_hi:[1,0]
	v_pk_mul_f32 v[38:39], v[38:39], v[226:227] op_sel_hi:[1,0]
	v_pk_mul_f32 v[40:41], v[40:41], v[226:227] op_sel_hi:[1,0]
	v_pk_mul_f32 v[42:43], v[42:43], v[226:227] op_sel_hi:[1,0]
	v_pk_mul_f32 v[44:45], v[44:45], v[226:227] op_sel_hi:[1,0]
	v_pk_mul_f32 v[46:47], v[46:47], v[226:227] op_sel_hi:[1,0]
	v_pk_mul_f32 v[44:45], v[144:145], v[44:45]
	v_pk_mul_f32 v[46:47], v[146:147], v[46:47]
	v_pk_mul_f32 v[40:41], v[148:149], v[40:41]
	v_pk_mul_f32 v[42:43], v[150:151], v[42:43]
	v_pk_mul_f32 v[36:37], v[152:153], v[36:37]
	v_pk_mul_f32 v[38:39], v[154:155], v[38:39]
	v_pk_mul_f32 v[32:33], v[156:157], v[32:33]
	v_pk_mul_f32 v[34:35], v[158:159], v[34:35]
	v_add_u32_e32 v246, 0x120000, v245
	global_store_dwordx4 v246, v[44:47], s[48:49]
	global_store_dwordx4 v246, v[40:43], s[48:49] offset:16
	global_store_dwordx4 v246, v[36:39], s[48:49] offset:512
	global_store_dwordx4 v246, v[32:35], s[48:49] offset:528
	v_mov_b32_e32 v226, v234
	v_pk_mul_f32 v[16:17], v[16:17], v[226:227] op_sel_hi:[1,0]
	v_pk_mul_f32 v[18:19], v[18:19], v[226:227] op_sel_hi:[1,0]
	v_pk_mul_f32 v[20:21], v[20:21], v[226:227] op_sel_hi:[1,0]
	v_pk_mul_f32 v[22:23], v[22:23], v[226:227] op_sel_hi:[1,0]
	v_pk_mul_f32 v[24:25], v[24:25], v[226:227] op_sel_hi:[1,0]
	v_pk_mul_f32 v[26:27], v[26:27], v[226:227] op_sel_hi:[1,0]
	v_pk_mul_f32 v[28:29], v[28:29], v[226:227] op_sel_hi:[1,0]
	v_pk_mul_f32 v[30:31], v[30:31], v[226:227] op_sel_hi:[1,0]
	v_pk_mul_f32 v[28:29], v[144:145], v[28:29]
	v_pk_mul_f32 v[30:31], v[146:147], v[30:31]
	v_pk_mul_f32 v[24:25], v[148:149], v[24:25]
	v_pk_mul_f32 v[26:27], v[150:151], v[26:27]
	v_pk_mul_f32 v[20:21], v[152:153], v[20:21]
	v_pk_mul_f32 v[22:23], v[154:155], v[22:23]
	v_pk_mul_f32 v[16:17], v[156:157], v[16:17]
	v_pk_mul_f32 v[18:19], v[158:159], v[18:19]
	v_add_u32_e32 v246, 0x140000, v245
	global_store_dwordx4 v246, v[28:31], s[48:49]
	global_store_dwordx4 v246, v[24:27], s[48:49] offset:16
	global_store_dwordx4 v246, v[20:23], s[48:49] offset:512
	global_store_dwordx4 v246, v[16:19], s[48:49] offset:528
	v_mov_b32_e32 v226, v235
	v_pk_mul_f32 v[0:1], v[0:1], v[226:227] op_sel_hi:[1,0]
	v_pk_mul_f32 v[2:3], v[2:3], v[226:227] op_sel_hi:[1,0]
	v_pk_mul_f32 v[4:5], v[4:5], v[226:227] op_sel_hi:[1,0]
	v_pk_mul_f32 v[6:7], v[6:7], v[226:227] op_sel_hi:[1,0]
	v_pk_mul_f32 v[8:9], v[8:9], v[226:227] op_sel_hi:[1,0]
	v_pk_mul_f32 v[10:11], v[10:11], v[226:227] op_sel_hi:[1,0]
	v_pk_mul_f32 v[12:13], v[12:13], v[226:227] op_sel_hi:[1,0]
	v_pk_mul_f32 v[14:15], v[14:15], v[226:227] op_sel_hi:[1,0]
	v_pk_mul_f32 v[12:13], v[144:145], v[12:13]
	v_pk_mul_f32 v[14:15], v[146:147], v[14:15]
	v_pk_mul_f32 v[8:9], v[148:149], v[8:9]
	v_pk_mul_f32 v[10:11], v[150:151], v[10:11]
	v_pk_mul_f32 v[4:5], v[152:153], v[4:5]
	v_pk_mul_f32 v[6:7], v[154:155], v[6:7]
	v_pk_mul_f32 v[0:1], v[156:157], v[0:1]
	v_pk_mul_f32 v[2:3], v[158:159], v[2:3]
	v_add_u32_e32 v246, 0x160000, v245
	s_andn2_b64 vcc, exec, s[4:5]
	s_mov_b64 s[4:5], -1
	global_store_dwordx4 v246, v[12:15], s[48:49]
	global_store_dwordx4 v246, v[8:11], s[48:49] offset:16
	global_store_dwordx4 v246, v[4:7], s[48:49] offset:512
	global_store_dwordx4 v246, v[0:3], s[48:49] offset:528
	s_cbranch_vccnz .LBB0_1348
	s_andn2_b64 vcc, exec, s[14:15]
	s_cbranch_vccnz .LBB0_1347
	s_barrier
	s_branch .LBB0_1347

	.amdhsa_kernel _Z6mk_fwd4Args
		.amdhsa_group_segment_fixed_size 0
		.amdhsa_private_segment_fixed_size 0
		.amdhsa_kernarg_size 448
		.amdhsa_user_sgpr_count 2
		.amdhsa_user_sgpr_dispatch_ptr 0
		.amdhsa_user_sgpr_queue_ptr 0
		.amdhsa_user_sgpr_kernarg_segment_ptr 1
		.amdhsa_user_sgpr_dispatch_id 0
		.amdhsa_user_sgpr_kernarg_preload_length 0
		.amdhsa_user_sgpr_kernarg_preload_offset 0
		.amdhsa_user_sgpr_private_segment_size 0
		.amdhsa_uses_dynamic_stack 0
		.amdhsa_enable_private_segment 0
		.amdhsa_system_sgpr_workgroup_id_x 1
		.amdhsa_system_sgpr_workgroup_id_y 0
		.amdhsa_system_sgpr_workgroup_id_z 0
		.amdhsa_system_sgpr_workgroup_info 0
		.amdhsa_system_vgpr_workitem_id 2
		.amdhsa_next_free_vgpr 256
		.amdhsa_next_free_sgpr 98
		.amdhsa_accum_offset 256
		.amdhsa_reserve_vcc 1
		.amdhsa_float_round_mode_32 0
		.amdhsa_float_round_mode_16_64 0
		.amdhsa_float_denorm_mode_32 3
		.amdhsa_float_denorm_mode_16_64 3
		.amdhsa_dx10_clamp 1
		.amdhsa_ieee_mode 1
		.amdhsa_fp16_overflow 0
		.amdhsa_tg_split 0
		.amdhsa_exception_fp_ieee_invalid_op 0
		.amdhsa_exception_fp_denorm_src 0
		.amdhsa_exception_fp_ieee_div_zero 0
		.amdhsa_exception_fp_ieee_overflow 0
		.amdhsa_exception_fp_ieee_underflow 0
		.amdhsa_exception_fp_ieee_inexact 0
		.amdhsa_exception_int_div_zero 0
	.end_amdhsa_kernel

.Lfunc_end0:
	.size	_Z6mk_fwd4Args, .Lfunc_end0-_Z6mk_fwd4Args
	.set _Z6mk_fwd4Args.num_vgpr, 256
	.set _Z6mk_fwd4Args.num_agpr, 0
	.set _Z6mk_fwd4Args.numbered_sgpr, 98
	.set _Z6mk_fwd4Args.num_named_barrier, 0
	.set _Z6mk_fwd4Args.private_seg_size, 0
	.set _Z6mk_fwd4Args.uses_vcc, 1
	.set _Z6mk_fwd4Args.uses_flat_scratch, 0
	.set _Z6mk_fwd4Args.has_dyn_sized_stack, 0
	.set _Z6mk_fwd4Args.has_recursion, 0
	.set _Z6mk_fwd4Args.has_indirect_call, 0

amdhsa.kernels:
  - .agpr_count:     0
    .args:
      - .offset:         0
        .size:           192
        .value_kind:     by_value
      - .offset:         192
        .size:           4
        .value_kind:     hidden_block_count_x
      - .offset:         196
        .size:           4
        .value_kind:     hidden_block_count_y
      - .offset:         200
        .size:           4
        .value_kind:     hidden_block_count_z
      - .offset:         204
        .size:           2
        .value_kind:     hidden_group_size_x
      - .offset:         206
        .size:           2
        .value_kind:     hidden_group_size_y
      - .offset:         208
        .size:           2
        .value_kind:     hidden_group_size_z
      - .offset:         210
        .size:           2
        .value_kind:     hidden_remainder_x
      - .offset:         212
        .size:           2
        .value_kind:     hidden_remainder_y
      - .offset:         214
        .size:           2
        .value_kind:     hidden_remainder_z
      - .offset:         232
        .size:           8
        .value_kind:     hidden_global_offset_x
      - .offset:         240
        .size:           8
        .value_kind:     hidden_global_offset_y
      - .offset:         248
        .size:           8
        .value_kind:     hidden_global_offset_z
      - .offset:         256
        .size:           2
        .value_kind:     hidden_grid_dims
      - .offset:         280
        .size:           8
        .value_kind:     hidden_multigrid_sync_arg
      - .offset:         312
        .size:           4
        .value_kind:     hidden_dynamic_lds_size
    .group_segment_fixed_size: 0
    .kernarg_segment_align: 8
    .kernarg_segment_size: 448
    .language:       OpenCL C
    .language_version:
      - 2
      - 0
    .max_flat_workgroup_size: 512
    .name:           _Z6mk_fwd4Args
    .private_segment_fixed_size: 0
    .sgpr_count:     104
    .sgpr_spill_count: 11
    .symbol:         _Z6mk_fwd4Args.kd
    .uniform_work_group_size: 1
    .uses_dynamic_stack: false
    .vgpr_count:     256
    .vgpr_spill_count: 0
    .wavefront_size: 64
